# feat_a: third-round LN units moved from workgroups 0..63 (five token iterations) to workgroups 128..191 (four token iterations)
# speedup vs baseline: 1.0072x; 1.0072x over previous
; DI void phase_feat_a(KP p, int l, char* lds) {
;     ...
;     for (int unit = 2 * blockIdx.x + hb; unit < (M / 64) * 2; unit += 2 * gridDim.x) {
;       const int grp = unit >> 1; const bool isv2 = unit & 1;
;       const int r0 = grp * 64; const int b = r0 / T, t0 = r0 % T;
.LBB0_261:
	s_or_b64 exec, exec, s[54:55]
	v_readlane_b32 s2, v253, 8
	s_waitcnt lgkmcnt(0)
	s_barrier
	v_add_u32_e32 v19, s2, v19
	v_add_u32_e32 v250, 0xfffffc00, v19
	v_mov_b32_e32 v251, 0x7fff
	v_cmp_gt_u32_e32 vcc, 0x80, v250
	s_nop 1
	v_cndmask_b32_e32 v19, v19, v251, vcc
	v_add_u32_e32 v250, 0xfffffb00, v19
	v_add_u32_e32 v251, 0xffffff00, v19
	v_cmp_gt_u32_e32 vcc, 0x80, v250
	s_nop 1
	v_cndmask_b32_e32 v19, v19, v251, vcc
	s_nop 1
	s_mov_b64 s[74:75], vcc
	s_movk_i32 s2, 0x47f
	v_cmp_lt_i32_e32 vcc, s2, v19
	v_readlane_b32 s2, v254, 54
	s_or_b64 s[4:5], vcc, s[4:5]
	s_nop 0
	v_add_u32_e32 v56, s2, v56
	v_add_u32_e32 v251, 0xffffe000, v56
	s_nop 0
	v_cndmask_b32_e64 v56, v56, v251, s[74:75]
	s_andn2_b64 exec, exec, s[4:5]
	s_cbranch_execz .LBB0_285
